# helper: drop the lgkmcnt(0) wait before publishing the ring flag (LDS ops of one wave execute in issue order, flag write still follows the data writes)
# speedup vs baseline: 1.0063x; 1.0063x over previous
.LBB0_182:
	s_min_u32 s4, s37, 0x1030
	s_lshl_b32 s4, s4, 2
	s_cmp_gt_u32 s37, 48
	s_cselect_b32 s5, 0xffffff3c, 60
	s_cselect_b32 s23, s10, s33
	s_cselect_b32 s37, s46, 0xfc
	s_add_i32 s44, s4, s5
	s_sub_i32 s37, s37, s44
	s_waitcnt vmcnt(38)
	s_and_b64 s[4:5], s[42:43], exec
	s_waitcnt vmcnt(36)
	v_fma_mix_f32 v188, v91, v2, v92 op_sel:[0,0,0] op_sel_hi:[1,0,0]
	v_fma_mix_f32 v189, v91, v3, v93 op_sel:[1,0,0] op_sel_hi:[1,0,0]
	v_fma_mix_f32 v190, v90, v0, v94 op_sel:[0,0,0] op_sel_hi:[1,0,0]
	v_fma_mix_f32 v191, v90, v1, v95 op_sel:[1,0,0] op_sel_hi:[1,0,0]
	v_fma_mix_f32 v192, v103, v188, 0 op_sel:[0,0,0] op_sel_hi:[1,0,0]
	v_fma_mix_f32 v193, v103, v189, 0 op_sel:[1,0,0] op_sel_hi:[1,0,0]
	v_fma_mix_f32 v194, v102, v190, 0 op_sel:[0,0,0] op_sel_hi:[1,0,0]
	v_fma_mix_f32 v195, v102, v191, 0 op_sel:[1,0,0] op_sel_hi:[1,0,0]
	s_cselect_b32 s4, s44, s37
	s_add_i32 s4, s4, s23
	s_ashr_i32 s5, s4, 31
	s_lshl_b64 s[4:5], s[4:5], 11
	v_add_u32_e32 v187, s4, v119
	v_pk_mul_f16 v123, v91, v35
	v_pk_mul_f16 v122, v90, v34
	v_cvt_pk_f16_f32 v125, v192, v193
	v_cvt_pk_f16_f32 v124, v194, v195
	ds_write_b128 v120, v[32:35] offset:21504
	ds_write_b128 v120, v[122:125] offset:22528
	s_waitcnt vmcnt(35)
	v_add_u32_e32 v185, v121, v186
	ds_write_b64 v185, v[100:101] offset:23552
	v_mov_b32_e32 v32, s22
	ds_write_b32 v161, v32 offset:49152
	global_load_dwordx2 v[32:33], v187, s[74:75]
	global_load_dwordx2 v[90:91], v187, s[76:77]
	global_load_dwordx2 v[34:35], v187, s[78:79]
	global_load_dwordx2 v[102:103], v187, s[80:81]
	global_load_dwordx2 v[100:101], v187, s[82:83]
	s_nop 0
	s_andn2_b64 vcc, exec, s[90:91]
	s_mov_b32 s37, s22
	s_cbranch_vccz .LBB0_242

; DEV void rwkv_helper(const Params& p, const Ctx& cx, int l, int unit, int lane, char* ring) {
;     ...
;   RH_LOAD(q0, 0); RH_LOAD(q1, 1); RH_LOAD(q2, 2); RH_LOAD(q3, 3); RH_LOAD(q4, 4); RH_LOAD(q5, 5); RH_LOAD(q6, 6); RH_LOAD(q7, 7);
; #pragma unroll 1
;   for (int g = 0; g < RW_NG; g += 8) {
;     RH_STEP(q0, g); RH_LOAD(q0, g + 8); __builtin_amdgcn_sched_barrier(0);
;     RH_STEP(q1, g + 1); RH_LOAD(q1, g + 9); __builtin_amdgcn_sched_barrier(0);
;     RH_STEP(q2, g + 2); RH_LOAD(q2, g + 10); __builtin_amdgcn_sched_barrier(0);
;     RH_STEP(q3, g + 3); RH_LOAD(q3, g + 11); __builtin_amdgcn_sched_barrier(0);
;     RH_STEP(q4, g + 4); RH_LOAD(q4, g + 12); __builtin_amdgcn_sched_barrier(0);
;     RH_STEP(q5, g + 5); RH_LOAD(q5, g + 13); __builtin_amdgcn_sched_barrier(0);
;     RH_STEP(q6, g + 6); RH_LOAD(q6, g + 14); __builtin_amdgcn_sched_barrier(0);
;     RH_STEP(q7, g + 7); RH_LOAD(q7, g + 15); __builtin_amdgcn_sched_barrier(0);
.LBB0_185:
	s_waitcnt vmcnt(38)
	s_waitcnt vmcnt(36)
	s_and_b32 s4, s37, 8
	s_mulk_i32 s4, 0xc00
	s_add_i32 s4, s4, 16
	s_or_b32 s23, s37, 1
	s_add_i32 s22, s37, 8
	s_cmpk_gt_u32 s37, 0x1037
	v_fma_mix_f32 v188, v36, v0, v94 op_sel:[0,0,0] op_sel_hi:[1,0,0]
	v_fma_mix_f32 v189, v36, v1, v95 op_sel:[1,0,0] op_sel_hi:[1,0,0]
	v_fma_mix_f32 v190, v37, v2, v92 op_sel:[0,0,0] op_sel_hi:[1,0,0]
	v_fma_mix_f32 v191, v37, v3, v93 op_sel:[1,0,0] op_sel_hi:[1,0,0]
	v_fma_mix_f32 v192, v44, v188, 0 op_sel:[0,0,0] op_sel_hi:[1,0,0]
	v_fma_mix_f32 v193, v44, v189, 0 op_sel:[1,0,0] op_sel_hi:[1,0,0]
	v_fma_mix_f32 v194, v45, v190, 0 op_sel:[0,0,0] op_sel_hi:[1,0,0]
	v_fma_mix_f32 v195, v45, v191, 0 op_sel:[1,0,0] op_sel_hi:[1,0,0]
	v_pk_mul_f16 v122, v36, v6
	v_cvt_pk_f16_f32 v124, v192, v193
	v_add_u32_e32 v36, s4, v113
	v_add_u32_e32 v121, s4, v111
	s_cselect_b64 s[90:91], -1, 0
	s_lshl_b32 s4, s22, 2
	s_cmpk_lt_u32 s37, 0x1038
	s_cselect_b32 s4, s4, 0x40fc
	s_add_i32 s5, s4, 0xffffff00
	s_min_u32 s44, s5, s4
	s_cmpk_gt_u32 s4, 0xff
	s_movk_i32 s4, 0x3fff
	s_cselect_b32 s4, s4, 0xff
	s_cselect_b32 s45, s10, s33
	s_sub_i32 s4, s4, s44
	s_add_i32 vcc_lo, s4, -3
	s_and_b64 s[4:5], s[42:43], exec
	s_cselect_b32 s4, s44, vcc_lo
	s_add_i32 s4, s4, s45
	s_ashr_i32 s5, s4, 31
	s_lshl_b64 s[4:5], s[4:5], 11
	v_add_u32_e32 v187, s4, v119
	v_add_u32_e32 v120, v36, v128
	v_pk_mul_f16 v123, v37, v7
	v_cvt_pk_f16_f32 v125, v194, v195
	ds_write_b128 v120, v[4:7]
	ds_write_b128 v120, v[122:125] offset:1024
	s_waitcnt vmcnt(35)
	v_add_u32_e32 v185, v121, v186
	ds_write_b64 v185, v[38:39] offset:2048
	v_mov_b32_e32 v4, s23
	ds_write_b32 v161, v4 offset:49152
	global_load_dwordx2 v[4:5], v187, s[74:75]
	global_load_dwordx2 v[36:37], v187, s[76:77]
	global_load_dwordx2 v[6:7], v187, s[78:79]
	global_load_dwordx2 v[44:45], v187, s[80:81]
	global_load_dwordx2 v[38:39], v187, s[82:83]
	s_nop 0
	v_cndmask_b32_e64 v122, 0, 1, s[92:93]
	v_cmp_ne_u32_e64 s[44:45], 1, v122
	s_andn2_b64 vcc, exec, s[92:93]
	s_cbranch_vccnz .LBB0_187
	s_add_i32 s4, s37, -14
	s_cmp_ge_i32 s36, s4
	s_cbranch_scc0 .LBB0_203
.LBB0_187:
	s_waitcnt vmcnt(38)
	s_waitcnt vmcnt(36)
	v_fma_mix_f32 v188, v41, v2, v92 op_sel:[0,0,0] op_sel_hi:[1,0,0]
	v_fma_mix_f32 v189, v41, v3, v93 op_sel:[1,0,0] op_sel_hi:[1,0,0]
	v_fma_mix_f32 v190, v40, v0, v94 op_sel:[0,0,0] op_sel_hi:[1,0,0]
	v_fma_mix_f32 v191, v40, v1, v95 op_sel:[1,0,0] op_sel_hi:[1,0,0]
	v_fma_mix_f32 v192, v53, v188, 0 op_sel:[0,0,0] op_sel_hi:[1,0,0]
	v_fma_mix_f32 v193, v53, v189, 0 op_sel:[1,0,0] op_sel_hi:[1,0,0]
	v_fma_mix_f32 v194, v52, v190, 0 op_sel:[0,0,0] op_sel_hi:[1,0,0]
	v_fma_mix_f32 v195, v52, v191, 0 op_sel:[1,0,0] op_sel_hi:[1,0,0]
	s_and_b32 s4, s23, 9
	s_mulk_i32 s4, 0xc00
	s_add_i32 s4, s4, 16
	v_pk_mul_f16 v122, v40, v10
	v_add3_u32 v40, s4, v113, v128
	v_pk_mul_f16 v123, v41, v11
	v_cvt_pk_f16_f32 v125, v192, v193
	v_cvt_pk_f16_f32 v124, v194, v195
	ds_write_b128 v40, v[8:11]
	ds_write_b128 v40, v[122:125] offset:1024
	v_add_u32_e32 v8, s4, v111
	s_or_b32 s4, s37, 2
	s_waitcnt vmcnt(35)
	v_add_u32_e32 v185, v8, v186
	ds_write_b64 v185, v[46:47] offset:2048
	v_mov_b32_e32 v8, s4
	s_min_u32 s4, s37, 0x1036
	s_lshl_b32 s4, s4, 2
	s_cmp_gt_u32 s37, 54
	s_cselect_b32 s5, 0xffffff24, 36
	s_cselect_b32 s23, s10, s33
	s_cselect_b32 s92, s46, 0xfc
	s_add_i32 s93, s4, s5
	s_sub_i32 s92, s92, s93
	s_and_b64 s[4:5], s[42:43], exec
	s_cselect_b32 s4, s93, s92
	s_add_i32 s4, s4, s23
	s_ashr_i32 s5, s4, 31
	s_lshl_b64 s[4:5], s[4:5], 11
	v_add_u32_e32 v187, s4, v119
	ds_write_b32 v161, v8 offset:49152
	global_load_dwordx2 v[8:9], v187, s[74:75]
	global_load_dwordx2 v[40:41], v187, s[76:77]
	global_load_dwordx2 v[10:11], v187, s[78:79]
	global_load_dwordx2 v[52:53], v187, s[80:81]
	global_load_dwordx2 v[46:47], v187, s[82:83]
	s_nop 0
	s_and_b64 vcc, exec, s[44:45]
	s_cbranch_vccnz .LBB0_189
	s_add_i32 s4, s37, -13
	s_cmp_ge_i32 s36, s4
	s_cbranch_scc0 .LBB0_206
.LBB0_189:
	s_waitcnt vmcnt(38)
	s_waitcnt vmcnt(36)
	v_fma_mix_f32 v188, v49, v2, v92 op_sel:[0,0,0] op_sel_hi:[1,0,0]
	v_fma_mix_f32 v189, v49, v3, v93 op_sel:[1,0,0] op_sel_hi:[1,0,0]
	v_fma_mix_f32 v190, v48, v0, v94 op_sel:[0,0,0] op_sel_hi:[1,0,0]
	v_fma_mix_f32 v191, v48, v1, v95 op_sel:[1,0,0] op_sel_hi:[1,0,0]
	v_fma_mix_f32 v192, v61, v188, 0 op_sel:[0,0,0] op_sel_hi:[1,0,0]
	v_fma_mix_f32 v193, v61, v189, 0 op_sel:[1,0,0] op_sel_hi:[1,0,0]
	v_fma_mix_f32 v194, v60, v190, 0 op_sel:[0,0,0] op_sel_hi:[1,0,0]
	v_fma_mix_f32 v195, v60, v191, 0 op_sel:[1,0,0] op_sel_hi:[1,0,0]
	s_or_b32 s4, s37, 3
	v_pk_mul_f16 v123, v49, v15
	v_pk_mul_f16 v122, v48, v14
	v_cvt_pk_f16_f32 v125, v192, v193
	v_cvt_pk_f16_f32 v124, v194, v195
	ds_write_b128 v120, v[12:15] offset:6144
	ds_write_b128 v120, v[122:125] offset:7168
	s_waitcnt vmcnt(35)
	v_add_u32_e32 v185, v121, v186
	ds_write_b64 v185, v[54:55] offset:8192
	v_mov_b32_e32 v12, s4
	s_min_u32 s4, s37, 0x1035
	s_lshl_b32 s4, s4, 2
	s_cmp_gt_u32 s37, 53
	s_cselect_b32 s5, 0xffffff28, 40
	s_cselect_b32 s23, s10, s33
	s_cselect_b32 s92, s46, 0xfc
	s_add_i32 s93, s4, s5
	s_sub_i32 s92, s92, s93
	s_and_b64 s[4:5], s[42:43], exec
	s_cselect_b32 s4, s93, s92
	s_add_i32 s4, s4, s23
	s_ashr_i32 s5, s4, 31
	s_lshl_b64 s[4:5], s[4:5], 11
	v_add_u32_e32 v187, s4, v119
	ds_write_b32 v161, v12 offset:49152
	global_load_dwordx2 v[12:13], v187, s[74:75]
	global_load_dwordx2 v[48:49], v187, s[76:77]
	global_load_dwordx2 v[14:15], v187, s[78:79]
	global_load_dwordx2 v[60:61], v187, s[80:81]
	global_load_dwordx2 v[54:55], v187, s[82:83]
	s_nop 0
	s_and_b64 vcc, exec, s[44:45]
	s_cbranch_vccnz .LBB0_191
	s_add_i32 s4, s37, -12
	s_cmp_ge_i32 s36, s4
	s_cbranch_scc0 .LBB0_209
; DEV void rwkv_helper(const Params& p, const Ctx& cx, int l, int unit, int lane, char* ring) {
;     ...
;   RH_LOAD(q0, 0); RH_LOAD(q1, 1); RH_LOAD(q2, 2); RH_LOAD(q3, 3); RH_LOAD(q4, 4); RH_LOAD(q5, 5); RH_LOAD(q6, 6); RH_LOAD(q7, 7);
; #pragma unroll 1
;   for (int g = 0; g < RW_NG; g += 8) {
;     RH_STEP(q0, g); RH_LOAD(q0, g + 8); __builtin_amdgcn_sched_barrier(0);
;     RH_STEP(q1, g + 1); RH_LOAD(q1, g + 9); __builtin_amdgcn_sched_barrier(0);
;     RH_STEP(q2, g + 2); RH_LOAD(q2, g + 10); __builtin_amdgcn_sched_barrier(0);
;     RH_STEP(q3, g + 3); RH_LOAD(q3, g + 11); __builtin_amdgcn_sched_barrier(0);
;     RH_STEP(q4, g + 4); RH_LOAD(q4, g + 12); __builtin_amdgcn_sched_barrier(0);
;     RH_STEP(q5, g + 5); RH_LOAD(q5, g + 13); __builtin_amdgcn_sched_barrier(0);
;     RH_STEP(q6, g + 6); RH_LOAD(q6, g + 14); __builtin_amdgcn_sched_barrier(0);
;     RH_STEP(q7, g + 7); RH_LOAD(q7, g + 15); __builtin_amdgcn_sched_barrier(0);
.LBB0_191:
	s_waitcnt vmcnt(38)
	s_waitcnt vmcnt(36)
	v_fma_mix_f32 v188, v57, v2, v92 op_sel:[0,0,0] op_sel_hi:[1,0,0]
	v_fma_mix_f32 v189, v57, v3, v93 op_sel:[1,0,0] op_sel_hi:[1,0,0]
	v_fma_mix_f32 v190, v56, v0, v94 op_sel:[0,0,0] op_sel_hi:[1,0,0]
	v_fma_mix_f32 v191, v56, v1, v95 op_sel:[1,0,0] op_sel_hi:[1,0,0]
	v_fma_mix_f32 v192, v67, v188, 0 op_sel:[0,0,0] op_sel_hi:[1,0,0]
	v_fma_mix_f32 v193, v67, v189, 0 op_sel:[1,0,0] op_sel_hi:[1,0,0]
	v_fma_mix_f32 v194, v66, v190, 0 op_sel:[0,0,0] op_sel_hi:[1,0,0]
	v_fma_mix_f32 v195, v66, v191, 0 op_sel:[1,0,0] op_sel_hi:[1,0,0]
	s_or_b32 s4, s37, 4
	v_pk_mul_f16 v123, v57, v19
	v_pk_mul_f16 v122, v56, v18
	v_cvt_pk_f16_f32 v125, v192, v193
	v_cvt_pk_f16_f32 v124, v194, v195
	ds_write_b128 v120, v[16:19] offset:9216
	ds_write_b128 v120, v[122:125] offset:10240
	s_waitcnt vmcnt(35)
	v_add_u32_e32 v185, v121, v186
	ds_write_b64 v185, v[62:63] offset:11264
	v_mov_b32_e32 v16, s4
	s_min_u32 s4, s37, 0x1034
	s_lshl_b32 s4, s4, 2
	s_cmp_gt_u32 s37, 52
	s_cselect_b32 s5, 0xffffff2c, 44
	s_cselect_b32 s23, s10, s33
	s_cselect_b32 s92, s46, 0xfc
	s_add_i32 s93, s4, s5
	s_sub_i32 s92, s92, s93
	s_and_b64 s[4:5], s[42:43], exec
	s_cselect_b32 s4, s93, s92
	s_add_i32 s4, s4, s23
	s_ashr_i32 s5, s4, 31
	s_lshl_b64 s[4:5], s[4:5], 11
	v_add_u32_e32 v187, s4, v119
	ds_write_b32 v161, v16 offset:49152
	global_load_dwordx2 v[16:17], v187, s[74:75]
	global_load_dwordx2 v[56:57], v187, s[76:77]
	global_load_dwordx2 v[18:19], v187, s[78:79]
	global_load_dwordx2 v[66:67], v187, s[80:81]
	global_load_dwordx2 v[62:63], v187, s[82:83]
	s_nop 0
	s_and_b64 vcc, exec, s[44:45]
	s_cbranch_vccnz .LBB0_193
	s_add_i32 s4, s37, -11
	s_cmp_ge_i32 s36, s4
	s_cbranch_scc0 .LBB0_212
.LBB0_193:
	s_waitcnt vmcnt(38)
	s_waitcnt vmcnt(36)
	v_fma_mix_f32 v188, v65, v2, v92 op_sel:[0,0,0] op_sel_hi:[1,0,0]
	v_fma_mix_f32 v189, v65, v3, v93 op_sel:[1,0,0] op_sel_hi:[1,0,0]
	v_fma_mix_f32 v190, v64, v0, v94 op_sel:[0,0,0] op_sel_hi:[1,0,0]
	v_fma_mix_f32 v191, v64, v1, v95 op_sel:[1,0,0] op_sel_hi:[1,0,0]
	v_fma_mix_f32 v192, v77, v188, 0 op_sel:[0,0,0] op_sel_hi:[1,0,0]
	v_fma_mix_f32 v193, v77, v189, 0 op_sel:[1,0,0] op_sel_hi:[1,0,0]
	v_fma_mix_f32 v194, v76, v190, 0 op_sel:[0,0,0] op_sel_hi:[1,0,0]
	v_fma_mix_f32 v195, v76, v191, 0 op_sel:[1,0,0] op_sel_hi:[1,0,0]
	s_or_b32 s4, s37, 5
	v_pk_mul_f16 v123, v65, v23
	v_pk_mul_f16 v122, v64, v22
	v_cvt_pk_f16_f32 v125, v192, v193
	v_cvt_pk_f16_f32 v124, v194, v195
	ds_write_b128 v120, v[20:23] offset:12288
	ds_write_b128 v120, v[122:125] offset:13312
	s_waitcnt vmcnt(35)
	v_add_u32_e32 v185, v121, v186
	ds_write_b64 v185, v[70:71] offset:14336
	v_mov_b32_e32 v20, s4
	s_min_u32 s4, s37, 0x1033
	s_lshl_b32 s4, s4, 2
	s_cmp_gt_u32 s37, 51
	s_cselect_b32 s5, 0xffffff30, 48
	s_cselect_b32 s23, s10, s33
	s_cselect_b32 s92, s46, 0xfc
	s_add_i32 s93, s4, s5
	s_sub_i32 s92, s92, s93
	s_and_b64 s[4:5], s[42:43], exec
	s_cselect_b32 s4, s93, s92
	s_add_i32 s4, s4, s23
	s_ashr_i32 s5, s4, 31
	s_lshl_b64 s[4:5], s[4:5], 11
	v_add_u32_e32 v187, s4, v119
	ds_write_b32 v161, v20 offset:49152
	global_load_dwordx2 v[20:21], v187, s[74:75]
	global_load_dwordx2 v[64:65], v187, s[76:77]
	global_load_dwordx2 v[22:23], v187, s[78:79]
	global_load_dwordx2 v[76:77], v187, s[80:81]
	global_load_dwordx2 v[70:71], v187, s[82:83]
	s_nop 0
	s_and_b64 vcc, exec, s[44:45]
	s_cbranch_vccnz .LBB0_195
	s_add_i32 s4, s37, -10
	s_cmp_ge_i32 s36, s4
	s_cbranch_scc0 .LBB0_215
.LBB0_195:
	s_waitcnt vmcnt(38)
	s_waitcnt vmcnt(36)
	v_fma_mix_f32 v188, v73, v2, v92 op_sel:[0,0,0] op_sel_hi:[1,0,0]
	v_fma_mix_f32 v189, v73, v3, v93 op_sel:[1,0,0] op_sel_hi:[1,0,0]
	v_fma_mix_f32 v190, v72, v0, v94 op_sel:[0,0,0] op_sel_hi:[1,0,0]
	v_fma_mix_f32 v191, v72, v1, v95 op_sel:[1,0,0] op_sel_hi:[1,0,0]
	v_fma_mix_f32 v192, v85, v188, 0 op_sel:[0,0,0] op_sel_hi:[1,0,0]
	v_fma_mix_f32 v193, v85, v189, 0 op_sel:[1,0,0] op_sel_hi:[1,0,0]
	v_fma_mix_f32 v194, v84, v190, 0 op_sel:[0,0,0] op_sel_hi:[1,0,0]
	v_fma_mix_f32 v195, v84, v191, 0 op_sel:[1,0,0] op_sel_hi:[1,0,0]
	s_or_b32 s4, s37, 6
	v_pk_mul_f16 v123, v73, v27
	v_pk_mul_f16 v122, v72, v26
	v_cvt_pk_f16_f32 v125, v192, v193
	v_cvt_pk_f16_f32 v124, v194, v195
	ds_write_b128 v120, v[24:27] offset:15360
	ds_write_b128 v120, v[122:125] offset:16384
	s_waitcnt vmcnt(35)
	v_add_u32_e32 v185, v121, v186
	ds_write_b64 v185, v[78:79] offset:17408
	v_mov_b32_e32 v24, s4
	s_min_u32 s4, s37, 0x1032
	s_lshl_b32 s4, s4, 2
	s_cmp_gt_u32 s37, 50
	s_cselect_b32 s5, 0xffffff34, 52
	s_cselect_b32 s23, s10, s33
	s_cselect_b32 s92, s46, 0xfc
	s_add_i32 s93, s4, s5
	s_sub_i32 s92, s92, s93
	s_and_b64 s[4:5], s[42:43], exec
	s_cselect_b32 s4, s93, s92
	s_add_i32 s4, s4, s23
	s_ashr_i32 s5, s4, 31
	s_lshl_b64 s[4:5], s[4:5], 11
	v_add_u32_e32 v187, s4, v119
	ds_write_b32 v161, v24 offset:49152
	global_load_dwordx2 v[24:25], v187, s[74:75]
	global_load_dwordx2 v[72:73], v187, s[76:77]
	global_load_dwordx2 v[26:27], v187, s[78:79]
	global_load_dwordx2 v[84:85], v187, s[80:81]
	global_load_dwordx2 v[78:79], v187, s[82:83]
	s_nop 0
	s_and_b64 vcc, exec, s[44:45]
	s_cbranch_vccnz .LBB0_197
	s_add_i32 s4, s37, -9
	s_cmp_ge_i32 s36, s4
	s_cbranch_scc0 .LBB0_218
.LBB0_197:
	s_waitcnt vmcnt(38)
	s_waitcnt vmcnt(36)
	v_fma_mix_f32 v188, v83, v2, v92 op_sel:[0,0,0] op_sel_hi:[1,0,0]
	v_fma_mix_f32 v189, v83, v3, v93 op_sel:[1,0,0] op_sel_hi:[1,0,0]
	v_fma_mix_f32 v190, v82, v0, v94 op_sel:[0,0,0] op_sel_hi:[1,0,0]
	v_fma_mix_f32 v191, v82, v1, v95 op_sel:[1,0,0] op_sel_hi:[1,0,0]
	v_fma_mix_f32 v192, v99, v188, 0 op_sel:[0,0,0] op_sel_hi:[1,0,0]
	v_fma_mix_f32 v193, v99, v189, 0 op_sel:[1,0,0] op_sel_hi:[1,0,0]
	v_fma_mix_f32 v194, v98, v190, 0 op_sel:[0,0,0] op_sel_hi:[1,0,0]
	v_fma_mix_f32 v195, v98, v191, 0 op_sel:[1,0,0] op_sel_hi:[1,0,0]
	s_or_b32 s4, s37, 7
	v_pk_mul_f16 v123, v83, v31
	v_pk_mul_f16 v122, v82, v30
	v_cvt_pk_f16_f32 v125, v192, v193
	v_cvt_pk_f16_f32 v124, v194, v195
	ds_write_b128 v120, v[28:31] offset:18432
	ds_write_b128 v120, v[122:125] offset:19456
	s_waitcnt vmcnt(35)
	v_add_u32_e32 v185, v121, v186
	ds_write_b64 v185, v[88:89] offset:20480
	v_mov_b32_e32 v28, s4
	s_min_u32 s4, s37, 0x1031
	s_lshl_b32 s4, s4, 2
	s_cmp_gt_u32 s37, 49
	s_cselect_b32 s5, 0xffffff38, 56
	s_cselect_b32 s23, s10, s33
	s_cselect_b32 s92, s46, 0xfc
	s_add_i32 s93, s4, s5
	s_sub_i32 s92, s92, s93
	s_and_b64 s[4:5], s[42:43], exec
	s_cselect_b32 s4, s93, s92
	s_add_i32 s4, s4, s23
	s_ashr_i32 s5, s4, 31
	s_lshl_b64 s[4:5], s[4:5], 11
	v_add_u32_e32 v187, s4, v119
	ds_write_b32 v161, v28 offset:49152
	global_load_dwordx2 v[28:29], v187, s[74:75]
	global_load_dwordx2 v[82:83], v187, s[76:77]
	global_load_dwordx2 v[30:31], v187, s[78:79]
	global_load_dwordx2 v[98:99], v187, s[80:81]
	global_load_dwordx2 v[88:89], v187, s[82:83]
	s_nop 0
	s_and_b64 vcc, exec, s[44:45]
	s_cbranch_vccnz .LBB0_182
	s_add_i32 s4, s37, -8
	s_cmp_ge_i32 s36, s4
	s_cbranch_scc0 .LBB0_221
	s_branch .LBB0_182
